# P8 prompt row pass: non-temporal loads (on top of P12 nt)
# baseline (speedup 1.0000x reference)
; __device__ __forceinline__ float wave_sum(float v) { for (int o = 32; o >= 1; o >>= 1) v += __shfl_xor(v, o); return v; }
; __device__ __forceinline__ f32x4 up4(u32x2 w) { return (f32x4){bf_lo(w.x), bf_hi(w.x), bf_lo(w.y), bf_hi(w.y)}; }
; __device__ __forceinline__ void row_pass1(const Args& a, int row_lo, int row_hi, int gw, int NGW, int lane) {
;     ...
;     for (int r0 = row_lo + 2 * gw; r0 < row_hi; r0 += 2 * NGW) {
;         f32x4 xv[2][4]; u32x2 yv[2][4]; float rs[2];
; #pragma unroll
;         for (int r = 0; r < 2; ++r) { const int row = (r0 + r < row_hi) ? r0 + r : r0; rs[r] = rss[row];
;             const f32x4* xr = (const f32x4*)xrow_ptr(a, row) + lane; const u32x2* yr = (const u32x2*)(Y + (size_t)row * DM) + lane;
; #pragma unroll
;             for (int j = 0; j < 4; ++j) { xv[r][j] = xr[64 * j]; yv[r][j] = yr[64 * j]; } }
; #pragma unroll
;         for (int r = 0; r < 2; ++r) { const int row = r0 + r; if (row >= row_hi) break;
;             const float rstd = rsqrtf(rs[r] * (1.f / DM) + EPS); f32x4 v[4]; float s = 0.f;
; #pragma unroll
;             for (int j = 0; j < 4; ++j) { v[j] = xv[r][j] + up4(yv[r][j]) * rstd * gp[j]; s += (v[j][0] * v[j][0] + v[j][1] * v[j][1]) + (v[j][2] * v[j][2] + v[j][3] * v[j][3]); }
;             const float rstd2 = rsqrtf(wave_sum(s) * (1.f / DM) + EPS);
.LBB0_1040:
	s_add_i32 s3, s8, 1
	s_cmpk_lt_i32 s3, 0x4000
	s_cselect_b32 s0, s3, s8
	s_ashr_i32 s1, s0, 31
	s_lshl_b64 s[28:29], s[0:1], 2
	s_add_u32 s28, s6, s28
	s_addc_u32 s29, s7, s29
	s_add_i32 s30, s0, 0xffffc000
	s_cmpk_lt_i32 s0, 0x4000
	v_readlane_b32 s36, v252, 1
	s_cselect_b32 s31, s1, 0
	s_cselect_b32 s30, s0, s30
	v_readlane_b32 s37, v252, 2
	v_readlane_b32 s38, v252, 3
	v_readlane_b32 s39, v252, 4
	s_cselect_b32 s33, s37, s39
	s_cselect_b32 s34, s36, s38
	s_lshl_b64 s[30:31], s[30:31], 12
	s_add_u32 s30, s34, s30
	v_lshl_add_u64 v[88:89], s[54:55], 0, v[50:51]
	s_addc_u32 s31, s33, s31
	s_lshl_b64 s[0:1], s[0:1], 11
	s_waitcnt vmcnt(12)
	v_add_co_u32_e32 v32, vcc, s11, v88
	s_add_u32 s34, s54, s9
	s_nop 0
	v_addc_co_u32_e32 v33, vcc, 0, v89, vcc
	s_addc_u32 s35, s55, s24
	global_load_dwordx2 v[84:85], v[32:33], off offset:1536 nt
	global_load_dwordx2 v[86:87], v[32:33], off offset:1024 nt
	global_load_dwordx2 v[90:91], v[32:33], off offset:512 nt
	global_load_dwordx2 v[92:93], v[32:33], off nt
	global_load_dword v101, v161, s[34:35]
	v_lshl_add_u64 v[32:33], s[22:23], 0, v[160:161]
	global_load_dwordx4 v[60:63], v[32:33], off nt
	global_load_dwordx4 v[72:75], v[32:33], off offset:1024 nt
	global_load_dwordx4 v[76:79], v[32:33], off offset:2048 nt
	global_load_dwordx4 v[80:83], v[32:33], off offset:3072 nt
	global_load_dword v71, v161, s[28:29]
	v_lshl_add_u64 v[94:95], v[48:49], 0, s[0:1]
	global_load_dwordx4 v[44:47], v160, s[30:31] nt
	global_load_dwordx4 v[40:43], v160, s[30:31] offset:1024 nt
	s_waitcnt lgkmcnt(0)
	global_load_dwordx4 v[36:39], v160, s[30:31] offset:2048 nt
	global_load_dwordx4 v[32:35], v160, s[30:31] offset:3072 nt
	global_load_dwordx2 v[58:59], v[94:95], off nt
	global_load_dwordx2 v[56:57], v[94:95], off offset:512 nt
	global_load_dwordx2 v[54:55], v[94:95], off offset:1024 nt
	global_load_dwordx2 v[52:53], v[94:95], off offset:1536 nt
	s_cmpk_gt_i32 s3, 0x3fff
	v_readlane_b32 s40, v252, 5
	v_readlane_b32 s41, v252, 6
	v_readlane_b32 s42, v252, 7
	v_readlane_b32 s43, v252, 8
	v_readlane_b32 s44, v252, 9
	v_readlane_b32 s45, v252, 10
	v_readlane_b32 s46, v252, 11
	v_readlane_b32 s47, v252, 12
	v_readlane_b32 s48, v252, 13
	v_readlane_b32 s49, v252, 14
	v_readlane_b32 s50, v252, 15
	v_readlane_b32 s51, v252, 16
	s_waitcnt vmcnt(17)
	v_lshlrev_b32_e32 v100, 16, v84
	s_waitcnt vmcnt(16)
	v_lshlrev_b32_e32 v98, 16, v86
	s_waitcnt vmcnt(15)
	v_lshlrev_b32_e32 v96, 16, v90
	s_waitcnt vmcnt(14)
	v_lshlrev_b32_e32 v94, 16, v92
	s_waitcnt vmcnt(13)
	v_fmamk_f32 v101, v101, 0x3a800000, v70
	v_mul_f32_e32 v102, 0x4b800000, v101
	v_cmp_gt_f32_e32 vcc, s25, v101
	v_and_b32_e32 v95, 0xffff0000, v92
	v_lshlrev_b32_e32 v92, 16, v93
	v_cndmask_b32_e32 v101, v101, v102, vcc
	v_rsq_f32_e32 v102, v101
	v_and_b32_e32 v93, 0xffff0000, v93
	v_and_b32_e32 v97, 0xffff0000, v90
	v_lshlrev_b32_e32 v90, 16, v91
	v_mul_f32_e32 v103, 0x45800000, v102
	v_and_b32_e32 v91, 0xffff0000, v91
	v_cndmask_b32_e32 v102, v102, v103, vcc
	v_and_b32_e32 v99, 0xffff0000, v86
	v_lshlrev_b32_e32 v86, 16, v87
	v_and_b32_e32 v87, 0xffff0000, v87
	v_and_b32_e32 v101, 0xffff0000, v84
	v_lshlrev_b32_e32 v84, 16, v85
	v_and_b32_e32 v85, 0xffff0000, v85
	v_pk_mul_f32 v[94:95], v[102:103], v[94:95] op_sel_hi:[0,1]
	v_pk_mul_f32 v[92:93], v[102:103], v[92:93] op_sel_hi:[0,1]
	v_pk_mul_f32 v[96:97], v[102:103], v[96:97] op_sel_hi:[0,1]
	v_pk_mul_f32 v[90:91], v[102:103], v[90:91] op_sel_hi:[0,1]
	v_pk_mul_f32 v[98:99], v[102:103], v[98:99] op_sel_hi:[0,1]
	v_pk_mul_f32 v[104:105], v[102:103], v[86:87] op_sel_hi:[0,1]
	v_pk_mul_f32 v[100:101], v[102:103], v[100:101] op_sel_hi:[0,1]
	v_pk_mul_f32 v[102:103], v[102:103], v[84:85] op_sel_hi:[0,1]
	s_waitcnt vmcnt(12)
	v_pk_fma_f32 v[86:87], v[2:3], v[92:93], v[62:63]
	v_pk_fma_f32 v[84:85], v[0:1], v[94:95], v[60:61]
	s_waitcnt vmcnt(11)
	v_pk_fma_f32 v[74:75], v[10:11], v[90:91], v[74:75]
	v_pk_fma_f32 v[72:73], v[8:9], v[96:97], v[72:73]
	v_pk_mul_f32 v[60:61], v[86:87], v[86:87]
	v_pk_mul_f32 v[62:63], v[84:85], v[84:85]
	v_pk_mul_f32 v[90:91], v[74:75], v[74:75]
	v_pk_mul_f32 v[92:93], v[72:73], v[72:73]
	s_waitcnt vmcnt(10)
	v_pk_fma_f32 v[78:79], v[18:19], v[104:105], v[78:79]
	v_pk_fma_f32 v[76:77], v[16:17], v[98:99], v[76:77]
	v_pk_mov_b32 v[98:99], v[62:63], v[60:61] op_sel:[1,0]
	v_mov_b32_e32 v63, v61
	v_pk_mov_b32 v[60:61], v[92:93], v[90:91] op_sel:[1,0]
	v_mov_b32_e32 v93, v91
	v_mul_f32_e32 v94, v76, v76
	v_mul_f32_e32 v96, v78, v78
	v_pk_add_f32 v[62:63], v[98:99], v[62:63]
	v_pk_add_f32 v[60:61], v[60:61], v[92:93]
	s_waitcnt vmcnt(9)
	v_pk_fma_f32 v[82:83], v[26:27], v[102:103], v[82:83]
	v_pk_fma_f32 v[80:81], v[24:25], v[100:101], v[80:81]
	v_pk_fma_f32 v[90:91], v[76:77], v[76:77], v[94:95] op_sel_hi:[1,1,0]
	v_pk_fma_f32 v[94:95], v[78:79], v[78:79], v[96:97] op_sel_hi:[1,1,0]
	v_pk_add_f32 v[62:63], v[62:63], v[62:63] op_sel_hi:[0,1]
	v_pk_add_f32 v[60:61], v[60:61], v[60:61] op_sel_hi:[0,1]
	v_mul_f32_e32 v90, v80, v80
	v_mul_f32_e32 v94, v81, v81
	v_mul_f32_e32 v62, v82, v82
	v_mul_f32_e32 v60, v83, v83
	v_pk_add_f32 v[90:91], v[90:91], v[94:95]
	v_pk_add_f32 v[60:61], v[62:63], v[60:61]
	v_lshl_add_u64 v[62:63], s[14:15], 0, v[160:161]
	v_pk_add_f32 v[60:61], v[90:91], v[60:61]
	global_store_dwordx4 v[62:63], v[84:87], off
	v_add_f32_e32 v60, v60, v61
	ds_bpermute_b32 v61, v64, v60
	s_waitcnt lgkmcnt(0)
	v_add_f32_e32 v60, v60, v61
	ds_bpermute_b32 v61, v65, v60
	s_waitcnt lgkmcnt(0)
	v_add_f32_e32 v60, v60, v61
	ds_bpermute_b32 v61, v66, v60
	s_waitcnt lgkmcnt(0)
	v_add_f32_e32 v60, v60, v61
	ds_bpermute_b32 v61, v67, v60
	s_waitcnt lgkmcnt(0)
; __device__ __forceinline__ float wave_sum(float v) { for (int o = 32; o >= 1; o >>= 1) v += __shfl_xor(v, o); return v; }
; __device__ __forceinline__ u32x2 pk4(f32x4 v) { u32x2 w; w.x = cvt_pk_bf16(v[0], v[1]); w.y = cvt_pk_bf16(v[2], v[3]); return w; }
; __device__ __forceinline__ void row_pass1(const Args& a, int row_lo, int row_hi, int gw, int NGW, int lane) {
;     ...
;             const float rstd2 = rsqrtf(wave_sum(s) * (1.f / DM) + EPS);
;             f32x4* xo = (f32x4*)(XO + (size_t)row * DM) + lane; u32x2* ao = (u32x2*)(A2 + (size_t)row * DM) + lane;
; #pragma unroll
;             for (int j = 0; j < 4; ++j) { xo[64 * j] = v[j]; ao[64 * j] = pk4(v[j] * rstd2 * gq[j]); } }
	v_add_f32_e32 v60, v60, v61
	ds_bpermute_b32 v61, v68, v60
	s_waitcnt lgkmcnt(0)
	v_add_f32_e32 v60, v60, v61
	ds_bpermute_b32 v61, v69, v60
	s_waitcnt lgkmcnt(0)
	v_add_f32_e32 v60, v60, v61
	v_fmamk_f32 v60, v60, 0x3a800000, v70
	v_mul_f32_e32 v61, 0x4b800000, v60
	v_cmp_gt_f32_e32 vcc, s25, v60
	s_nop 1
	v_cndmask_b32_e32 v60, v60, v61, vcc
	v_rsq_f32_e32 v90, v60
	v_add_co_u32_e64 v60, s[0:1], s26, v88
	v_mul_f32_e32 v88, 0x45800000, v90
	v_cndmask_b32_e32 v88, v90, v88, vcc
	v_addc_co_u32_e64 v61, s[0:1], 0, v89, s[0:1]
	v_pk_mul_f32 v[84:85], v[84:85], v[88:89] op_sel_hi:[1,0]
	v_pk_mul_f32 v[86:87], v[86:87], v[88:89] op_sel_hi:[1,0]
	v_pk_mul_f32 v[90:91], v[72:73], v[88:89] op_sel_hi:[1,0]
	v_pk_mul_f32 v[92:93], v[74:75], v[88:89] op_sel_hi:[1,0]
	v_pk_mul_f32 v[94:95], v[76:77], v[88:89] op_sel_hi:[1,0]
	v_pk_mul_f32 v[96:97], v[78:79], v[88:89] op_sel_hi:[1,0]
	v_pk_mul_f32 v[98:99], v[80:81], v[88:89] op_sel_hi:[1,0]
	v_pk_mul_f32 v[88:89], v[82:83], v[88:89] op_sel_hi:[1,0]
	v_pk_mul_f32 v[86:87], v[6:7], v[86:87]
	v_pk_mul_f32 v[84:85], v[4:5], v[84:85]
	v_pk_mul_f32 v[92:93], v[14:15], v[92:93]
	v_pk_mul_f32 v[88:89], v[30:31], v[88:89]
	v_pk_mul_f32 v[98:99], v[28:29], v[98:99]
	v_pk_mul_f32 v[90:91], v[12:13], v[90:91]
	v_pk_mul_f32 v[96:97], v[22:23], v[96:97]
	v_pk_mul_f32 v[94:95], v[20:21], v[94:95]
	v_cvt_pk_bf16_f32 v84, v84, v85
	v_cvt_pk_bf16_f32 v85, v86, v87
	v_cvt_pk_bf16_f32 v87, v92, v93
	v_cvt_pk_bf16_f32 v92, v98, v99
	v_cvt_pk_bf16_f32 v93, v88, v89
	v_cvt_pk_bf16_f32 v86, v90, v91
	v_cvt_pk_bf16_f32 v90, v94, v95
	v_cvt_pk_bf16_f32 v91, v96, v97
	global_store_dwordx2 v[60:61], v[84:85], off
	global_store_dwordx4 v[62:63], v[72:75], off offset:1024
	global_store_dwordx2 v[60:61], v[86:87], off offset:512
	global_store_dwordx4 v[62:63], v[76:79], off offset:2048
	global_store_dwordx2 v[60:61], v[90:91], off offset:1024
	global_store_dwordx4 v[62:63], v[80:83], off offset:3072
	global_store_dwordx2 v[60:61], v[92:93], off offset:1536
	s_cbranch_scc1 .LBB0_1039
; __device__ __forceinline__ float wave_sum(float v) { for (int o = 32; o >= 1; o >>= 1) v += __shfl_xor(v, o); return v; }
; __device__ __forceinline__ u32x2 pk4(f32x4 v) { u32x2 w; w.x = cvt_pk_bf16(v[0], v[1]); w.y = cvt_pk_bf16(v[2], v[3]); return w; }
; __device__ __forceinline__ f32x4 up4(u32x2 w) { return (f32x4){bf_lo(w.x), bf_hi(w.x), bf_lo(w.y), bf_hi(w.y)}; }
; __device__ __forceinline__ void row_pass1(const Args& a, int row_lo, int row_hi, int gw, int NGW, int lane) {
;     ...
;         for (int r = 0; r < 2; ++r) { const int row = r0 + r; if (row >= row_hi) break;
;             const float rstd = rsqrtf(rs[r] * (1.f / DM) + EPS); f32x4 v[4]; float s = 0.f;
; #pragma unroll
;             for (int j = 0; j < 4; ++j) { v[j] = xv[r][j] + up4(yv[r][j]) * rstd * gp[j]; s += (v[j][0] * v[j][0] + v[j][1] * v[j][1]) + (v[j][2] * v[j][2] + v[j][3] * v[j][3]); }
;             const float rstd2 = rsqrtf(wave_sum(s) * (1.f / DM) + EPS);
;             f32x4* xo = (f32x4*)(XO + (size_t)row * DM) + lane; u32x2* ao = (u32x2*)(A2 + (size_t)row * DM) + lane;
; #pragma unroll
;             for (int j = 0; j < 4; ++j) { xo[64 * j] = v[j]; ao[64 * j] = pk4(v[j] * rstd2 * gq[j]); } }
	s_waitcnt vmcnt(16)
	v_fmamk_f32 v71, v71, 0x3a800000, v70
	v_mul_f32_e32 v72, 0x4b800000, v71
	v_cmp_gt_f32_e32 vcc, s25, v71
	s_waitcnt vmcnt(11)
	v_and_b32_e32 v73, 0xffff0000, v58
	v_lshlrev_b32_e32 v74, 16, v59
	v_cndmask_b32_e32 v71, v71, v72, vcc
	v_rsq_f32_e32 v71, v71
	v_lshlrev_b32_e32 v72, 16, v58
	v_and_b32_e32 v75, 0xffff0000, v59
	v_mul_f32_e32 v58, 0x45800000, v71
	v_cndmask_b32_e32 v58, v71, v58, vcc
	v_pk_mul_f32 v[72:73], v[58:59], v[72:73] op_sel_hi:[0,1]
	v_pk_mul_f32 v[74:75], v[58:59], v[74:75] op_sel_hi:[0,1]
	v_pk_fma_f32 v[46:47], v[2:3], v[74:75], v[46:47]
	v_pk_fma_f32 v[44:45], v[0:1], v[72:73], v[44:45]
	v_pk_mul_f32 v[72:73], v[46:47], v[46:47]
	v_pk_mul_f32 v[74:75], v[44:45], v[44:45]
	s_nop 0
	v_pk_mov_b32 v[76:77], v[74:75], v[72:73] op_sel:[1,0]
	v_mov_b32_e32 v75, v73
	v_pk_add_f32 v[72:73], v[76:77], v[74:75]
	s_waitcnt vmcnt(10)
	v_lshlrev_b32_e32 v74, 16, v56
	v_and_b32_e32 v75, 0xffff0000, v56
	v_lshlrev_b32_e32 v56, 16, v57
	v_and_b32_e32 v57, 0xffff0000, v57
	v_pk_mul_f32 v[74:75], v[58:59], v[74:75] op_sel_hi:[0,1]
	v_pk_mul_f32 v[56:57], v[58:59], v[56:57] op_sel_hi:[0,1]
	v_pk_fma_f32 v[42:43], v[10:11], v[56:57], v[42:43]
	v_pk_fma_f32 v[40:41], v[8:9], v[74:75], v[40:41]
	v_pk_mul_f32 v[56:57], v[42:43], v[42:43]
	v_pk_mul_f32 v[74:75], v[40:41], v[40:41]
	s_nop 0
	v_pk_mov_b32 v[76:77], v[74:75], v[56:57] op_sel:[1,0]
	v_mov_b32_e32 v75, v57
	v_pk_add_f32 v[56:57], v[76:77], v[74:75]
	s_waitcnt vmcnt(9)
	v_lshlrev_b32_e32 v74, 16, v54
	v_and_b32_e32 v75, 0xffff0000, v54
	v_lshlrev_b32_e32 v54, 16, v55
	v_and_b32_e32 v55, 0xffff0000, v55
	v_pk_mul_f32 v[54:55], v[58:59], v[54:55] op_sel_hi:[0,1]
	v_pk_fma_f32 v[38:39], v[18:19], v[54:55], v[38:39]
	s_waitcnt vmcnt(8)
	v_lshlrev_b32_e32 v54, 16, v52
	v_and_b32_e32 v55, 0xffff0000, v52
	v_lshlrev_b32_e32 v52, 16, v53
	v_and_b32_e32 v53, 0xffff0000, v53
	v_pk_mul_f32 v[54:55], v[58:59], v[54:55] op_sel_hi:[0,1]
	v_pk_mul_f32 v[52:53], v[58:59], v[52:53] op_sel_hi:[0,1]
	v_pk_fma_f32 v[32:33], v[24:25], v[54:55], v[32:33]
	v_pk_fma_f32 v[34:35], v[26:27], v[52:53], v[34:35]
	v_mul_f32_e32 v54, v32, v32
	v_pk_add_f32 v[52:53], v[72:73], v[72:73] op_sel:[0,1] op_sel_hi:[1,0]
	v_pk_mul_f32 v[74:75], v[58:59], v[74:75] op_sel_hi:[0,1]
	v_mul_f32_e32 v58, v33, v33
	v_mov_b32_e32 v53, v54
	v_pk_add_f32 v[54:55], v[56:57], v[56:57] op_sel:[0,1] op_sel_hi:[1,0]
	v_pk_fma_f32 v[36:37], v[16:17], v[74:75], v[36:37]
	v_mov_b32_e32 v55, v58
	v_pk_add_f32 v[52:53], v[52:53], v[54:55]
	v_mul_f32_e32 v54, v37, v37
	v_mul_f32_e32 v56, v39, v39
	v_mul_f32_e32 v59, v34, v34
	v_mul_f32_e32 v71, v35, v35
	v_pk_fma_f32 v[54:55], v[36:37], v[36:37], v[54:55] op_sel_hi:[1,1,0]
	v_pk_fma_f32 v[56:57], v[38:39], v[38:39], v[56:57] op_sel_hi:[1,1,0]
	v_mov_b32_e32 v55, v59
	v_mov_b32_e32 v57, v71
	v_pk_add_f32 v[54:55], v[54:55], v[56:57]
	s_nop 0
	v_pk_add_f32 v[52:53], v[52:53], v[54:55]
	s_nop 0
	v_add_f32_e32 v52, v52, v53
	ds_bpermute_b32 v53, v64, v52
	s_waitcnt lgkmcnt(0)
	v_add_f32_e32 v52, v52, v53
	ds_bpermute_b32 v53, v65, v52
	s_waitcnt lgkmcnt(0)
	v_add_f32_e32 v52, v52, v53
	ds_bpermute_b32 v53, v66, v52
	s_waitcnt lgkmcnt(0)
	v_add_f32_e32 v52, v52, v53
	ds_bpermute_b32 v53, v67, v52
	s_waitcnt lgkmcnt(0)
	v_add_f32_e32 v52, v52, v53
	ds_bpermute_b32 v53, v68, v52
	s_waitcnt lgkmcnt(0)
	v_add_f32_e32 v52, v52, v53
	ds_bpermute_b32 v53, v69, v52
	s_waitcnt lgkmcnt(0)
	v_add_f32_e32 v52, v52, v53
	v_fmamk_f32 v52, v52, 0x3a800000, v70
	v_mul_f32_e32 v53, 0x4b800000, v52
	v_cmp_gt_f32_e32 vcc, s25, v52
	s_nop 1
	v_cndmask_b32_e32 v52, v52, v53, vcc
	v_rsq_f32_e32 v52, v52
	s_nop 0
	v_mul_f32_e32 v53, 0x45800000, v52
	v_cndmask_b32_e32 v52, v52, v53, vcc
	v_add_co_u32_e32 v54, vcc, s27, v62
	s_nop 1
	v_addc_co_u32_e32 v55, vcc, 0, v63, vcc
	global_store_dwordx4 v[54:55], v[44:47], off
	s_nop 1
	v_pk_mul_f32 v[44:45], v[44:45], v[52:53] op_sel_hi:[1,0]
	v_pk_mul_f32 v[46:47], v[46:47], v[52:53] op_sel_hi:[1,0]
	v_pk_mul_f32 v[44:45], v[4:5], v[44:45]
	v_pk_mul_f32 v[46:47], v[6:7], v[46:47]
	v_cvt_pk_bf16_f32 v44, v44, v45
	v_cvt_pk_bf16_f32 v45, v46, v47
	global_store_dwordx2 v[60:61], v[44:45], off offset:2048
	global_store_dwordx4 v[54:55], v[40:43], off offset:1024
	s_nop 1
	v_pk_mul_f32 v[40:41], v[40:41], v[52:53] op_sel_hi:[1,0]
	v_pk_mul_f32 v[42:43], v[42:43], v[52:53] op_sel_hi:[1,0]
	v_pk_mul_f32 v[40:41], v[12:13], v[40:41]
	v_pk_mul_f32 v[42:43], v[14:15], v[42:43]
	v_cvt_pk_bf16_f32 v40, v40, v41
	v_cvt_pk_bf16_f32 v41, v42, v43
	global_store_dwordx2 v[60:61], v[40:41], off offset:2560
	global_store_dwordx4 v[54:55], v[36:39], off offset:2048
	s_nop 1
	v_pk_mul_f32 v[36:37], v[36:37], v[52:53] op_sel_hi:[1,0]
	v_pk_mul_f32 v[38:39], v[38:39], v[52:53] op_sel_hi:[1,0]
	v_pk_mul_f32 v[36:37], v[20:21], v[36:37]
	v_pk_mul_f32 v[38:39], v[22:23], v[38:39]
	v_cvt_pk_bf16_f32 v36, v36, v37
	v_cvt_pk_bf16_f32 v37, v38, v39
	global_store_dwordx2 v[60:61], v[36:37], off offset:3072
	global_store_dwordx4 v[54:55], v[32:35], off offset:3072
	s_nop 1
	v_pk_mul_f32 v[32:33], v[32:33], v[52:53] op_sel_hi:[1,0]
	v_pk_mul_f32 v[34:35], v[34:35], v[52:53] op_sel_hi:[1,0]
	v_pk_mul_f32 v[32:33], v[28:29], v[32:33]
	v_pk_mul_f32 v[34:35], v[30:31], v[34:35]
	v_cvt_pk_bf16_f32 v32, v32, v33
	v_cvt_pk_bf16_f32 v33, v34, v35
	global_store_dwordx2 v[60:61], v[32:33], off offset:3584
	s_branch .LBB0_1039
